# attention prompt units: gate prefetch as 4 dwordx4 (was 8 dwordx2) + permlane16_swap restore, counted waits lowered by 4
# baseline (speedup 1.0000x reference)
.LBB0_548:
	s_mul_hi_i32 s0, s6, 0x7e07e07f
	s_lshr_b32 s1, s0, 31
	s_ashr_i32 s0, s0, 8
	s_add_i32 s0, s0, s1
	s_mul_i32 s1, s0, 0xfffffdf8
	s_add_i32 s7, s6, s1
	s_mul_hi_i32 s1, s7, 0x7e07e07f
	s_lshr_b32 s4, s1, 31
	s_ashr_i32 s1, s1, 5
	s_add_i32 s1, s1, s4
	s_mul_i32 s4, s1, 0xffffffbf
	s_add_i32 s4, s7, s4
	s_lshl_b32 s70, s4, 5
	s_mulk_i32 s0, 0x810
	s_lshl_b32 s5, s1, 3
	s_add_i32 s60, s70, s0
	s_add_i32 s5, s5, s68
	v_or_b32_e32 v0, s60, v103
	s_lshl_b32 s44, s5, 6
	s_ashr_i32 s45, s44, 31
	v_ashrrev_i32_e32 v1, 31, v0
	s_lshl_b64 s[0:1], s[44:45], 1
	v_lshlrev_b64 v[112:113], 13, v[0:1]
	v_add_u32_e32 v0, 16, v0
	v_lshl_add_u64 v[28:29], v[82:83], 0, s[0:1]
	v_ashrrev_i32_e32 v1, 31, v0
	v_lshl_add_u64 v[40:41], v[84:85], 0, s[0:1]
	v_lshl_add_u64 v[30:31], v[28:29], 0, v[112:113]
	v_lshlrev_b64 v[0:1], 13, v[0:1]
	global_load_dwordx4 v[36:39], v[30:31], off
	global_load_dwordx4 v[72:75], v[30:31], off offset:64
	v_lshl_add_u64 v[30:31], v[40:41], 0, v[112:113]
	v_lshl_add_u64 v[28:29], v[28:29], 0, v[0:1]
	v_lshl_add_u64 v[0:1], v[40:41], 0, v[0:1]
	v_mbcnt_lo_u32_b32 v40, -1, 0
	v_mbcnt_hi_u32_b32 v40, -1, v40
	v_and_b32_e32 v40, 16, v40
	v_lshrrev_b32_e32 v41, 1, v40
	v_lshl_add_u32 v40, v40, 1, v41
	v_sub_u32_e32 v40, 32, v40
	v_ashrrev_i32_e32 v41, 31, v40
	v_lshl_add_u64 v[30:31], v[40:41], 0, v[30:31]
	global_load_dwordx4 v[108:111], v[30:31], off
	global_load_dwordx4 v[104:107], v[30:31], off offset:64
	global_load_dwordx4 v[32:35], v[28:29], off
	s_nop 0
	global_load_dwordx4 v[28:31], v[28:29], off offset:64
	s_nop 0
	v_lshl_add_u64 v[0:1], v[40:41], 0, v[0:1]
	global_load_dwordx4 v[98:101], v[0:1], off
	global_load_dwordx4 v[94:97], v[0:1], off offset:64
	s_mul_i32 s0, s7, 0xfc1
	s_lshr_b32 s1, s0, 31
	s_ashr_i32 s0, s0, 18
	s_add_i32 s0, s0, s1
	s_mulk_i32 s0, 0x41
	s_sub_i32 s0, s7, s0
	s_waitcnt lgkmcnt(0)
	s_barrier
	s_sext_i32_i16 s0, s0
	s_lshl_b32 s0, s0, 5
	v_readlane_b32 s2, v255, 3
	s_sub_i32 s7, 0x7f, s0
	v_readlane_b32 s3, v255, 4
	s_and_saveexec_b64 s[0:1], s[2:3]
	s_cbranch_execz .LBB0_550
	v_cmp_lt_i32_e32 vcc, s7, v81
	s_waitcnt vmcnt(13)
	s_nop 0
	v_cndmask_b32_e32 v7, 0, v7, vcc
	v_cndmask_b32_e32 v6, 0, v6, vcc
	v_cndmask_b32_e32 v5, 0, v5, vcc
	v_cndmask_b32_e32 v4, 0, v4, vcc
	v_cmp_lt_i32_e32 vcc, s7, v147
	ds_write_b128 v156, v[4:7]
	s_waitcnt vmcnt(12)
	v_cndmask_b32_e32 v7, 0, v11, vcc
	v_cndmask_b32_e32 v6, 0, v10, vcc
	v_cndmask_b32_e32 v5, 0, v9, vcc
	v_cndmask_b32_e32 v4, 0, v8, vcc
	ds_write_b128 v157, v[4:7] offset:23040
.LBB0_550:
	s_or_b64 exec, exec, s[0:1]
	v_readlane_b32 s2, v255, 5
	v_readlane_b32 s3, v255, 6
	s_and_saveexec_b64 s[0:1], s[2:3]
	s_cbranch_execz .LBB0_552
	v_cmp_lt_i32_e32 vcc, s7, v148
	s_waitcnt vmcnt(11)
	s_nop 0
	v_cndmask_b32_e32 v7, 0, v15, vcc
	v_cndmask_b32_e32 v6, 0, v14, vcc
	v_cndmask_b32_e32 v5, 0, v13, vcc
	v_cndmask_b32_e32 v4, 0, v12, vcc
	v_cmp_lt_i32_e32 vcc, s7, v149
	ds_write_b128 v158, v[4:7]
	s_waitcnt vmcnt(10)
	v_cndmask_b32_e32 v7, 0, v19, vcc
	v_cndmask_b32_e32 v6, 0, v18, vcc
	v_cndmask_b32_e32 v5, 0, v17, vcc
	v_cndmask_b32_e32 v4, 0, v16, vcc
	ds_write_b128 v159, v[4:7] offset:23040
.LBB0_552:
	s_or_b64 exec, exec, s[0:1]
	v_readlane_b32 s2, v255, 7
	v_readlane_b32 s3, v255, 8
	s_and_saveexec_b64 s[0:1], s[2:3]
	s_cbranch_execz .LBB0_554
	v_cmp_lt_i32_e32 vcc, s7, v150
	s_waitcnt vmcnt(9)
	s_nop 0
	v_cndmask_b32_e32 v7, 0, v23, vcc
	v_cndmask_b32_e32 v6, 0, v22, vcc
	v_cndmask_b32_e32 v5, 0, v21, vcc
	v_cndmask_b32_e32 v4, 0, v20, vcc
	v_cmp_lt_i32_e32 vcc, s7, v151
	ds_write_b128 v161, v[4:7]
	s_waitcnt vmcnt(8)
	v_cndmask_b32_e32 v7, 0, v27, vcc
	v_cndmask_b32_e32 v6, 0, v26, vcc
	v_cndmask_b32_e32 v5, 0, v25, vcc
	v_cndmask_b32_e32 v4, 0, v24, vcc
	ds_write_b128 v166, v[4:7] offset:23040
.LBB0_554:
	s_or_b64 exec, exec, s[0:1]
	s_add_i32 s46, s6, s92
	s_cmpk_gt_i32 s46, 0x81f
	s_cselect_b64 s[2:3], -1, 0
	s_cmpk_lt_i32 s46, 0x820
	s_cselect_b32 s0, s46, s6
	s_mul_hi_i32 s1, s0, 0x7e07e07f
	s_lshr_b32 s6, s1, 31
	s_ashr_i32 s1, s1, 8
	s_add_i32 s1, s1, s6
	s_mul_i32 s6, s1, 0xfffffdf8
	s_add_i32 s6, s6, s0
	s_mul_hi_i32 s0, s6, 0x7e07e07f
	s_lshr_b32 s7, s0, 31
	s_ashr_i32 s0, s0, 5
	s_add_i32 s7, s0, s7
	s_mul_i32 s0, s7, 0xffffffbf
	s_add_i32 s0, s0, s6
	s_lshl_b32 s0, s0, 5
	s_add_i32 s12, s0, 0xffffff80
	s_lshl_b32 s6, s7, 6
	v_add_u32_e32 v0, s12, v138
	s_mul_i32 s0, s1, 0x810
	s_ashr_i32 s7, s6, 31
	v_max_i32_e32 v0, 0, v0
	s_lshl_b64 s[8:9], s[6:7], 1
	v_readlane_b32 s10, v252, 25
	v_add_u32_e32 v0, s0, v0
	v_readlane_b32 s11, v252, 26
	s_add_u32 s8, s10, s8
	v_ashrrev_i32_e32 v1, 31, v0
	s_addc_u32 s9, s11, s9
	v_lshlrev_b64 v[0:1], 10, v[0:1]
	v_lshl_add_u64 v[0:1], s[8:9], 0, v[0:1]
	v_mov_b32_e32 v89, v2
	v_lshl_add_u64 v[0:1], v[0:1], 0, v[88:89]
	global_load_dwordx4 v[4:7], v[0:1], off
	v_add_u32_e32 v0, s12, v140
	v_max_i32_e32 v3, 0, v0
	s_waitcnt vmcnt(13)
	v_lshlrev_b32_e32 v10, 1, v3
	v_add_u32_e32 v3, s12, v141
	v_max_i32_e32 v3, 0, v3
	s_waitcnt vmcnt(12)
	v_add_u32_e32 v12, s0, v3
	v_add_u32_e32 v3, s12, v143
	s_ashr_i32 s1, s0, 31
	v_max_i32_e32 v3, 0, v3
	s_lshl_b64 s[10:11], s[0:1], 1
	v_readlane_b32 s14, v252, 31
	s_waitcnt vmcnt(11)
	v_lshlrev_b32_e32 v18, 1, v3
	v_add_u32_e32 v3, s12, v144
	v_readlane_b32 s15, v252, 32
	s_add_u32 s10, s14, s10
	v_max_i32_e32 v3, 0, v3
	s_addc_u32 s11, s15, s11
	s_waitcnt vmcnt(10)
	v_add_u32_e32 v20, s0, v3
	v_add_u32_e32 v3, s12, v146
	v_add_u32_e32 v8, s6, v139
	v_mov_b64_e32 v[0:1], s[10:11]
	v_add_u32_e32 v16, s6, v142
	v_max_i32_e32 v3, 0, v3
	s_waitcnt vmcnt(9)
	v_add_u32_e32 v24, s6, v145
	v_mad_i64_i32 v[8:9], s[10:11], v8, s93, v[0:1]
	v_mov_b32_e32 v11, v2
	v_mad_i64_i32 v[16:17], s[10:11], v16, s93, v[0:1]
	v_mad_i64_i32 v[0:1], s[0:1], v24, s93, v[0:1]
	v_lshlrev_b32_e32 v24, 1, v3
	v_mov_b32_e32 v25, v2
	v_lshl_add_u64 v[8:9], v[8:9], 0, v[10:11]
	v_lshl_add_u64 v[0:1], v[0:1], 0, v[24:25]
	s_add_i32 s0, s5, 1
	global_load_dwordx4 v[8:11], v[8:9], off
	v_ashrrev_i32_e32 v13, 31, v12
	global_load_dwordx4 v[24:27], v[0:1], off
	v_cvt_f32_i32_e32 v0, s0
	v_ashrrev_i32_e32 v21, 31, v20
	v_lshlrev_b64 v[12:13], 10, v[12:13]
	v_lshlrev_b64 v[20:21], 10, v[20:21]
	v_mul_f32_e32 v1, 0xbe000000, v0
	v_cmp_gt_f32_e32 vcc, s94, v1
	s_and_b64 s[0:1], vcc, exec
	s_cselect_b32 s0, 0xffffffc0, 0
	v_cndmask_b32_e32 v1, 0, v213, vcc
	v_fmac_f32_e32 v1, 0xbe000000, v0
	v_exp_f32_e32 v0, v1
	v_lshl_add_u64 v[12:13], s[8:9], 0, v[12:13]
	v_lshl_add_u64 v[20:21], s[8:9], 0, v[20:21]
	v_readlane_b32 s8, v251, 4
	v_ldexp_f32 v0, v0, s0
	v_readlane_b32 s0, v255, 9
	s_add_i32 s0, s5, s0
	s_ashr_i32 s1, s0, 31
	v_mov_b32_e32 v91, v2
	v_mov_b32_e32 v19, v2
	v_mov_b32_e32 v93, v2
	s_lshl_b64 s[0:1], s[0:1], 2
	v_readlane_b32 s22, v251, 18
	v_lshl_add_u64 v[12:13], v[12:13], 0, v[90:91]
	v_lshl_add_u64 v[16:17], v[16:17], 0, v[18:19]
	v_lshl_add_u64 v[20:21], v[20:21], 0, v[92:93]
	v_readlane_b32 s23, v251, 19
	s_add_u32 s0, s22, s0
	global_load_dwordx4 v[12:15], v[12:13], off
	s_addc_u32 s1, s23, s1
	global_load_dwordx4 v[16:19], v[16:17], off
	v_mul_f32_e32 v102, 0x3fb8aa3b, v0
	global_load_dwordx4 v[20:23], v[20:21], off
	s_waitcnt lgkmcnt(0)
	s_barrier
	global_load_dword v1, v2, s[0:1]
	ds_read_b128 v[40:43], v170
	ds_read_b128 v[44:47], v170 offset:64
	s_waitcnt vmcnt(14) lgkmcnt(1)
	v_mfma_f32_16x16x32_bf16 v[40:43], v[40:43], v[36:39], 0
	v_or_b32_e32 v0, s70, v78
	s_cmp_lt_i32 s4, 4
	s_mov_b32 s50, s92
	s_waitcnt vmcnt(13) lgkmcnt(0)
	v_mfma_f32_16x16x32_bf16 v[48:51], v[44:47], v[72:75], v[40:43]
	s_nop 2
	ds_read_b128 v[40:43], v170 offset:2304
	ds_read_b128 v[44:47], v170 offset:2368
	v_readlane_b32 s9, v251, 5
	v_readlane_b32 s10, v251, 6
	s_waitcnt lgkmcnt(1)
	v_mfma_f32_16x16x32_bf16 v[40:43], v[40:43], v[36:39], 0
	v_readlane_b32 s11, v251, 7
	v_readlane_b32 s12, v251, 8
	v_readlane_b32 s13, v251, 9
	s_waitcnt lgkmcnt(0)
	v_mfma_f32_16x16x32_bf16 v[68:71], v[44:47], v[72:75], v[40:43]
	v_readlane_b32 s14, v251, 10
	v_readlane_b32 s15, v251, 11
	v_readlane_b32 s16, v251, 12
	v_readlane_b32 s17, v251, 13
	v_readlane_b32 s18, v251, 14
	v_readlane_b32 s19, v251, 15
	v_readlane_b32 s20, v251, 16
	v_readlane_b32 s21, v251, 17
	v_sub_u32_e32 v172, 0x80, v0
	s_cselect_b64 s[54:55], -1, 0
	ds_read_b128 v[40:43], v170 offset:4608
	ds_read_b128 v[44:47], v170 offset:4672
	s_waitcnt lgkmcnt(1)
	v_mfma_f32_16x16x32_bf16 v[40:43], v[40:43], v[36:39], 0
	s_waitcnt lgkmcnt(0)
	v_mfma_f32_16x16x32_bf16 v[64:67], v[44:47], v[72:75], v[40:43]
	s_nop 5
	ds_read_b128 v[40:43], v170 offset:6912
	ds_read_b128 v[44:47], v170 offset:6976
	s_waitcnt lgkmcnt(1)
	v_mfma_f32_16x16x32_bf16 v[40:43], v[40:43], v[36:39], 0
	s_waitcnt lgkmcnt(0)
	v_mfma_f32_16x16x32_bf16 v[60:63], v[44:47], v[72:75], v[40:43]
	s_nop 5
	ds_read_b128 v[40:43], v170 offset:9216
	ds_read_b128 v[44:47], v170 offset:9280
	s_waitcnt lgkmcnt(1)
	v_mfma_f32_16x16x32_bf16 v[40:43], v[40:43], v[36:39], 0
	s_waitcnt lgkmcnt(0)
	v_mfma_f32_16x16x32_bf16 v[56:59], v[44:47], v[72:75], v[40:43]
	s_nop 5
	ds_read_b128 v[40:43], v170 offset:11520
	ds_read_b128 v[44:47], v170 offset:11584
	s_waitcnt lgkmcnt(1)
	v_mfma_f32_16x16x32_bf16 v[40:43], v[40:43], v[36:39], 0
	s_waitcnt lgkmcnt(0)
	v_mfma_f32_16x16x32_bf16 v[52:55], v[44:47], v[72:75], v[40:43]
	s_nop 5
	ds_read_b128 v[40:43], v170 offset:13824
	ds_read_b128 v[44:47], v170 offset:13888
	s_waitcnt lgkmcnt(1)
	v_mfma_f32_16x16x32_bf16 v[40:43], v[40:43], v[36:39], 0
	s_waitcnt lgkmcnt(0)
	v_mfma_f32_16x16x32_bf16 v[44:47], v[44:47], v[72:75], v[40:43]
	s_nop 5
	ds_read_b128 v[40:43], v170 offset:16128
	ds_read_b128 v[114:117], v170 offset:16192
	s_waitcnt lgkmcnt(1)
	v_mfma_f32_16x16x32_bf16 v[40:43], v[40:43], v[36:39], 0
	s_waitcnt lgkmcnt(0)
	v_mfma_f32_16x16x32_bf16 v[40:43], v[114:117], v[72:75], v[40:43]
	ds_read_b128 v[114:117], v170 offset:18432
	ds_read_b128 v[118:121], v170 offset:18496
	s_movk_i32 s56, 0x63
	v_cmp_gt_i32_e64 s[92:93], s56, v172
	s_movk_i32 s56, 0x64
	s_waitcnt lgkmcnt(1)
	v_mfma_f32_16x16x32_bf16 v[36:39], v[114:117], v[36:39], 0
	v_cmp_gt_i32_e64 s[94:95], s56, v172
	s_movk_i32 s56, 0x71
	s_movk_i32 s4, 0x41
	v_cmp_gt_i32_e64 s[88:89], s56, v172
	s_movk_i32 s56, 0x72
	v_cmp_gt_i32_e64 s[16:17], s4, v172
	s_movk_i32 s4, 0x42
	v_cmp_gt_i32_e64 s[90:91], s56, v172
	s_movk_i32 s56, 0x73
	v_cmp_gt_i32_e64 s[18:19], s4, v172
	s_movk_i32 s4, 0x43
	v_cmp_gt_i32_e64 s[84:85], s56, v172
	s_movk_i32 s56, 0x74
	s_waitcnt lgkmcnt(0)
	v_mfma_f32_16x16x32_bf16 v[36:39], v[118:121], v[72:75], v[36:39]
	v_cmp_gt_i32_e64 s[12:13], s4, v172
	s_movk_i32 s4, 0x44
	v_cmp_gt_i32_e64 s[86:87], s56, v172
	s_movk_i32 s56, 0x81
	v_cmp_gt_i32_e64 s[14:15], s4, v172
	s_movk_i32 s4, 0x51
	v_cmp_gt_i32_e64 s[82:83], s56, v172
	s_movk_i32 s56, 0x83
	v_cmp_gt_i32_e64 s[8:9], s4, v172
	s_movk_i32 s4, 0x52
	s_movk_i32 s42, 0x61
	v_cmp_gt_i32_e64 s[80:81], s56, v172
	s_movk_i32 s56, 0x82
	v_mul_f32_e32 v0, v102, v152
	v_cmp_gt_i32_e64 s[10:11], s4, v172
	s_movk_i32 s4, 0x53
	s_movk_i32 s6, 0x54
	v_cmp_gt_i32_e64 s[96:97], s42, v172
	s_movk_i32 s42, 0x62
	v_cmp_gt_i32_e64 s[78:79], s56, v172
	s_movk_i32 s56, 0x84
	s_mov_b64 s[58:59], -1
	s_and_b64 vcc, exec, s[54:55]
	v_cmp_gt_i32_e64 s[38:39], 17, v172
	v_cmp_gt_i32_e64 s[40:41], 18, v172
	v_cmp_gt_i32_e64 s[36:37], 19, v172
	v_cmp_gt_i32_e64 s[52:53], 20, v172
	v_cmp_gt_i32_e64 s[34:35], 33, v172
	v_cmp_gt_i32_e64 s[0:1], 34, v172
	v_cmp_gt_i32_e64 s[26:27], 35, v172
	v_cmp_gt_i32_e64 s[30:31], 36, v172
	v_cmp_gt_i32_e64 s[24:25], 49, v172
	v_cmp_gt_i32_e64 s[28:29], 50, v172
	v_cmp_gt_i32_e64 s[20:21], 51, v172
	v_cmp_gt_i32_e64 s[22:23], 52, v172
	v_cmp_gt_i32_e64 s[4:5], s4, v172
	v_cmp_gt_i32_e64 s[6:7], s6, v172
	v_cmp_gt_i32_e64 s[42:43], s42, v172
	v_cmp_gt_i32_e64 s[76:77], s56, v172
	v_sub_f32_e32 v174, v48, v0
	v_sub_f32_e32 v173, v49, v0
	v_sub_f32_e32 v93, v36, v0
	s_cbranch_vccz .LBB0_556
	v_readlane_b32 s56, v255, 10
	v_cmp_gt_i32_e32 vcc, 1, v172
	v_readlane_b32 s57, v255, 11
	v_fma_f32 v3, 0, v102, v174
	s_and_b64 vcc, s[56:57], vcc
	v_readlane_b32 s56, v255, 12
	v_cndmask_b32_e32 v3, v214, v3, vcc
	v_cmp_gt_i32_e32 vcc, 2, v172
	v_readlane_b32 s57, v255, 13
	s_and_b64 vcc, s[56:57], vcc
	s_mov_b32 s56, 2.0
	s_waitcnt vmcnt(0)
	v_pk_add_f32 v[48:49], v[50:51], v[0:1] op_sel_hi:[1,0] neg_lo:[0,1] neg_hi:[0,1]
	s_mov_b32 s57, 0x40400000
	v_add_f32_e32 v36, v102, v173
	v_pk_fma_f32 v[48:49], v[102:103], s[56:57], v[48:49] op_sel_hi:[0,1,1]
	v_readlane_b32 s56, v255, 14
	v_cndmask_b32_e32 v36, v214, v36, vcc
	v_cmp_gt_i32_e32 vcc, 4, v172
	v_readlane_b32 s57, v255, 15
	s_and_b64 vcc, s[56:57], vcc
	v_readlane_b32 s56, v255, 16
	v_cndmask_b32_e32 v89, v214, v49, vcc
	v_cmp_gt_i32_e32 vcc, 3, v172
	v_readlane_b32 s57, v255, 17
	s_and_b64 vcc, s[56:57], vcc
	s_mov_b32 s56, 0x41800000
	v_cndmask_b32_e32 v91, v214, v48, vcc
	v_pk_add_f32 v[48:49], v[68:69], v[0:1] op_sel_hi:[1,0] neg_lo:[0,1] neg_hi:[0,1]
	s_mov_b32 s57, 0x41880000
	v_pk_fma_f32 v[48:49], v[102:103], s[56:57], v[48:49] op_sel_hi:[0,1,1]
	v_cndmask_b32_e64 v48, v214, v48, s[38:39]
	s_mov_b32 s38, 0x41900000
	v_pk_add_f32 v[72:73], v[70:71], v[0:1] op_sel_hi:[1,0] neg_lo:[0,1] neg_hi:[0,1]
	s_mov_b32 s39, 0x41980000
	v_pk_fma_f32 v[72:73], v[102:103], s[38:39], v[72:73] op_sel_hi:[0,1,1]
	v_cndmask_b32_e64 v72, v214, v72, s[36:37]
	s_mov_b32 s36, 0x42000000
	v_pk_add_f32 v[74:75], v[64:65], v[0:1] op_sel_hi:[1,0] neg_lo:[0,1] neg_hi:[0,1]
	s_mov_b32 s37, 0x42040000
	v_pk_fma_f32 v[74:75], v[102:103], s[36:37], v[74:75] op_sel_hi:[0,1,1]
	v_cndmask_b32_e64 v75, v214, v75, s[0:1]
	s_mov_b32 s0, 0x42080000
	v_max_f32_e32 v118, 0xf149f2ca, v3
	v_pk_add_f32 v[114:115], v[66:67], v[0:1] op_sel_hi:[1,0] neg_lo:[0,1] neg_hi:[0,1]
	s_mov_b32 s1, 0x420c0000
	v_max3_f32 v118, v118, v36, v91
	v_cndmask_b32_e64 v49, v214, v49, s[40:41]
	v_pk_fma_f32 v[114:115], v[102:103], s[0:1], v[114:115] op_sel_hi:[0,1,1]
	s_mov_b32 s0, 0x42400000
	v_max3_f32 v118, v118, v89, v48
	v_cndmask_b32_e64 v73, v214, v73, s[52:53]
	v_cndmask_b32_e64 v74, v214, v74, s[34:35]
	v_pk_add_f32 v[116:117], v[60:61], v[0:1] op_sel_hi:[1,0] neg_lo:[0,1] neg_hi:[0,1]
	s_mov_b32 s1, 0x42440000
	v_max3_f32 v118, v118, v49, v72
	v_cndmask_b32_e64 v114, v214, v114, s[26:27]
	v_pk_fma_f32 v[116:117], v[102:103], s[0:1], v[116:117] op_sel_hi:[0,1,1]
	v_max3_f32 v118, v118, v73, v74
	v_cndmask_b32_e64 v115, v214, v115, s[30:31]
	v_max3_f32 v118, v118, v75, v114
	v_cndmask_b32_e64 v116, v214, v116, s[24:25]
	s_mov_b32 s0, 0x42480000
	v_max3_f32 v120, v118, v115, v116
	v_pk_add_f32 v[118:119], v[62:63], v[0:1] op_sel_hi:[1,0] neg_lo:[0,1] neg_hi:[0,1]
	s_mov_b32 s1, 0x424c0000
	v_pk_fma_f32 v[118:119], v[102:103], s[0:1], v[118:119] op_sel_hi:[0,1,1]
	v_cndmask_b32_e64 v117, v214, v117, s[28:29]
	v_cndmask_b32_e64 v118, v214, v118, s[20:21]
	s_mov_b32 s0, 0x42800000
	v_max3_f32 v122, v120, v117, v118
	v_pk_add_f32 v[120:121], v[56:57], v[0:1] op_sel_hi:[1,0] neg_lo:[0,1] neg_hi:[0,1]
	s_mov_b32 s1, 0x42820000
	v_pk_fma_f32 v[120:121], v[102:103], s[0:1], v[120:121] op_sel_hi:[0,1,1]
	v_cndmask_b32_e64 v119, v214, v119, s[22:23]
	v_cndmask_b32_e64 v120, v214, v120, s[16:17]
	s_mov_b32 s0, 0x42840000
	v_max3_f32 v124, v122, v119, v120
	v_pk_add_f32 v[122:123], v[58:59], v[0:1] op_sel_hi:[1,0] neg_lo:[0,1] neg_hi:[0,1]
	s_mov_b32 s1, 0x42860000
	v_pk_fma_f32 v[122:123], v[102:103], s[0:1], v[122:123] op_sel_hi:[0,1,1]
	v_cndmask_b32_e64 v121, v214, v121, s[18:19]
	v_cndmask_b32_e64 v122, v214, v122, s[12:13]
	s_mov_b32 s0, 0x42a00000
	v_max3_f32 v126, v124, v121, v122
	v_pk_add_f32 v[124:125], v[52:53], v[0:1] op_sel_hi:[1,0] neg_lo:[0,1] neg_hi:[0,1]
	s_mov_b32 s1, 0x42a20000
	v_pk_fma_f32 v[124:125], v[102:103], s[0:1], v[124:125] op_sel_hi:[0,1,1]
	v_cndmask_b32_e64 v123, v214, v123, s[14:15]
	v_cndmask_b32_e64 v124, v214, v124, s[8:9]
	s_mov_b32 s0, 0x42a40000
	v_max3_f32 v128, v126, v123, v124
	v_pk_add_f32 v[126:127], v[54:55], v[0:1] op_sel_hi:[1,0] neg_lo:[0,1] neg_hi:[0,1]
	s_mov_b32 s1, 0x42a60000
	v_pk_fma_f32 v[126:127], v[102:103], s[0:1], v[126:127] op_sel_hi:[0,1,1]
	v_cndmask_b32_e64 v125, v214, v125, s[10:11]
	v_cndmask_b32_e64 v126, v214, v126, s[4:5]
	s_mov_b32 s0, 0x42c00000
	v_max3_f32 v130, v128, v125, v126
	v_pk_add_f32 v[128:129], v[44:45], v[0:1] op_sel_hi:[1,0] neg_lo:[0,1] neg_hi:[0,1]
	s_mov_b32 s1, 0x42c20000
	v_pk_fma_f32 v[128:129], v[102:103], s[0:1], v[128:129] op_sel_hi:[0,1,1]
	v_cndmask_b32_e64 v127, v214, v127, s[6:7]
	v_cndmask_b32_e64 v128, v214, v128, s[96:97]
	s_mov_b32 s0, 0x42c40000
	v_max3_f32 v132, v130, v127, v128
	v_pk_add_f32 v[130:131], v[46:47], v[0:1] op_sel_hi:[1,0] neg_lo:[0,1] neg_hi:[0,1]
	s_mov_b32 s1, 0x42c60000
	v_pk_fma_f32 v[130:131], v[102:103], s[0:1], v[130:131] op_sel_hi:[0,1,1]
	v_cndmask_b32_e64 v129, v214, v129, s[42:43]
	v_cndmask_b32_e64 v130, v214, v130, s[92:93]
	s_mov_b32 s0, 0x42e00000
	v_max3_f32 v134, v132, v129, v130
	v_pk_add_f32 v[132:133], v[40:41], v[0:1] op_sel_hi:[1,0] neg_lo:[0,1] neg_hi:[0,1]
	s_mov_b32 s1, 0x42e20000
	v_pk_fma_f32 v[132:133], v[102:103], s[0:1], v[132:133] op_sel_hi:[0,1,1]
	v_cndmask_b32_e64 v131, v214, v131, s[94:95]
	v_cndmask_b32_e64 v132, v214, v132, s[88:89]
	s_mov_b32 s0, 0x42e40000
	v_max3_f32 v162, v134, v131, v132
	v_pk_add_f32 v[134:135], v[42:43], v[0:1] op_sel_hi:[1,0] neg_lo:[0,1] neg_hi:[0,1]
	s_mov_b32 s1, 0x42e60000
	v_pk_fma_f32 v[134:135], v[102:103], s[0:1], v[134:135] op_sel_hi:[0,1,1]
	v_readlane_b32 s0, v255, 18
	v_readlane_b32 s1, v255, 19
	v_cndmask_b32_e64 v133, v214, v133, s[90:91]
	v_cndmask_b32_e64 v134, v214, v134, s[84:85]
	v_fmamk_f32 v163, v102, 0x43000000, v93
	s_and_b64 vcc, s[0:1], s[82:83]
	v_cndmask_b32_e64 v135, v214, v135, s[86:87]
	v_max3_f32 v162, v162, v133, v134
	v_cndmask_b32_e32 v175, v214, v163, vcc
	v_max3_f32 v178, v162, v135, v175
	v_mov_b32_e32 v162, v37
	v_mov_b32_e32 v163, v38
	s_mov_b32 s0, 0x43010000
	v_pk_add_f32 v[162:163], v[162:163], v[0:1] op_sel_hi:[1,0] neg_lo:[0,1] neg_hi:[0,1]
	s_mov_b32 s1, 0x43020000
	v_pk_fma_f32 v[162:163], v[102:103], s[0:1], v[162:163] op_sel_hi:[0,1,1]
	v_readlane_b32 s0, v255, 20
	v_readlane_b32 s1, v255, 21
	s_and_b64 vcc, s[0:1], s[80:81]
	v_readlane_b32 s0, v255, 22
	v_readlane_b32 s1, v255, 23
	v_cndmask_b32_e32 v176, v214, v163, vcc
	s_and_b64 vcc, s[0:1], s[78:79]
	v_readlane_b32 s0, v255, 24
	v_cndmask_b32_e32 v177, v214, v162, vcc
	v_readlane_b32 s1, v255, 25
	v_max3_f32 v178, v178, v177, v176
	s_and_b64 s[56:57], s[0:1], s[76:77]
	s_mov_b64 s[58:59], 0

.LBB0_558:
	v_and_b32_e32 v38, 64, v208
	v_xor_b32_e32 v37, 16, v208
	v_add_u32_e32 v38, 64, v38
	v_cmp_lt_i32_e32 vcc, v37, v38
	v_sub_f32_e32 v0, v39, v0
	v_fmac_f32_e32 v0, 0x43030000, v102
	v_cndmask_b32_e32 v37, v208, v37, vcc
	v_lshlrev_b32_e32 v173, 2, v37
	v_cndmask_b32_e64 v0, v214, v0, s[56:57]
	v_max_f32_e32 v37, v178, v178
	v_max_f32_e32 v37, v37, v0
	ds_bpermute_b32 v39, v173, v37
	v_xor_b32_e32 v40, 32, v208
	v_cmp_lt_i32_e32 vcc, v40, v38
	s_waitcnt vmcnt(0)
	v_mul_f32_e32 v67, 0x3fb8aa3b, v1
	v_add_u32_e32 v93, 0x5800, v171
	v_cndmask_b32_e32 v38, v208, v40, vcc
	v_lshlrev_b32_e32 v174, 2, v38
	s_waitcnt lgkmcnt(0)
	v_max_f32_e32 v38, v39, v39
	v_max_f32_e32 v37, v37, v38
	ds_bpermute_b32 v38, v174, v37
	s_mov_b32 s92, s50
	s_movk_i32 s93, 0x4400
	s_mov_b32 s94, 0xc2fc0000
	v_lshl_add_u64 v[64:65], s[44:45], 1, v[86:87]
	s_waitcnt lgkmcnt(0)
	v_max3_f32 v52, v37, v38, v67
	v_sub_f32_e32 v1, v3, v52
	v_exp_f32_e32 v1, v1
	v_sub_f32_e32 v3, v36, v52
	v_exp_f32_e32 v3, v3
	v_sub_f32_e32 v36, v91, v52
	v_exp_f32_e32 v41, v36
	v_sub_f32_e32 v37, v89, v52
	v_exp_f32_e32 v42, v37
	v_sub_f32_e32 v37, v48, v52
	v_add_f32_e32 v36, 0, v1
	v_exp_f32_e32 v43, v37
	v_sub_f32_e32 v37, v49, v52
	v_add_f32_e32 v36, v3, v36
	v_exp_f32_e32 v48, v37
	v_sub_f32_e32 v37, v72, v52
	v_add_f32_e32 v36, v41, v36
	v_exp_f32_e32 v49, v37
	v_sub_f32_e32 v37, v73, v52
	v_add_f32_e32 v36, v42, v36
	v_exp_f32_e32 v50, v37
	v_sub_f32_e32 v37, v74, v52
	v_add_f32_e32 v36, v43, v36
	v_exp_f32_e32 v55, v37
	v_sub_f32_e32 v37, v75, v52
	v_add_f32_e32 v36, v48, v36
	v_exp_f32_e32 v60, v37
	v_sub_f32_e32 v37, v114, v52
	v_add_f32_e32 v36, v49, v36
	v_exp_f32_e32 v61, v37
	v_sub_f32_e32 v37, v115, v52
	v_add_f32_e32 v36, v50, v36
	v_exp_f32_e32 v62, v37
	v_sub_f32_e32 v37, v116, v52
	v_add_f32_e32 v36, v55, v36
	v_exp_f32_e32 v63, v37
	v_sub_f32_e32 v37, v117, v52
	v_add_f32_e32 v36, v60, v36
	v_exp_f32_e32 v66, v37
	v_sub_f32_e32 v37, v118, v52
	v_add_f32_e32 v36, v61, v36
	v_exp_f32_e32 v68, v37
	v_sub_f32_e32 v37, v119, v52
	v_add_f32_e32 v36, v62, v36
	v_exp_f32_e32 v69, v37
	v_sub_f32_e32 v37, v120, v52
	v_add_f32_e32 v36, v63, v36
	v_exp_f32_e32 v70, v37
	v_sub_f32_e32 v37, v121, v52
	v_add_f32_e32 v36, v66, v36
	v_exp_f32_e32 v71, v37
	v_sub_f32_e32 v37, v122, v52
	v_add_f32_e32 v36, v68, v36
	v_exp_f32_e32 v72, v37
	v_sub_f32_e32 v37, v123, v52
	v_add_f32_e32 v36, v69, v36
	v_exp_f32_e32 v73, v37
	v_sub_f32_e32 v37, v124, v52
	v_add_f32_e32 v36, v70, v36
	v_exp_f32_e32 v74, v37
	v_sub_f32_e32 v37, v125, v52
	v_add_f32_e32 v36, v71, v36
	v_exp_f32_e32 v75, v37
	v_sub_f32_e32 v37, v126, v52
	v_add_f32_e32 v36, v72, v36
	v_exp_f32_e32 v114, v37
	v_sub_f32_e32 v37, v127, v52
	v_add_f32_e32 v36, v73, v36
	v_exp_f32_e32 v115, v37
	v_sub_f32_e32 v37, v128, v52
	v_add_f32_e32 v36, v74, v36
	v_exp_f32_e32 v116, v37
	v_sub_f32_e32 v37, v129, v52
	v_add_f32_e32 v36, v75, v36
	v_exp_f32_e32 v117, v37
	v_sub_f32_e32 v37, v130, v52
	v_add_f32_e32 v36, v114, v36
	v_exp_f32_e32 v118, v37
	v_sub_f32_e32 v37, v131, v52
	v_add_f32_e32 v36, v115, v36
	v_exp_f32_e32 v119, v37
	v_sub_f32_e32 v37, v132, v52
	v_add_f32_e32 v36, v116, v36
	v_exp_f32_e32 v120, v37
	v_sub_f32_e32 v37, v133, v52
	v_add_f32_e32 v36, v117, v36
	v_exp_f32_e32 v121, v37
	v_sub_f32_e32 v37, v134, v52
	v_add_f32_e32 v36, v118, v36
	v_exp_f32_e32 v122, v37
	v_sub_f32_e32 v37, v135, v52
	v_add_f32_e32 v36, v119, v36
	v_exp_f32_e32 v123, v37
	v_sub_f32_e32 v37, v175, v52
	v_add_f32_e32 v36, v120, v36
	v_exp_f32_e32 v125, v37
	v_sub_f32_e32 v37, v177, v52
	v_add_f32_e32 v36, v121, v36
	v_exp_f32_e32 v126, v37
	v_sub_f32_e32 v37, v176, v52
	v_add_f32_e32 v36, v122, v36
	v_exp_f32_e32 v127, v37
	v_sub_f32_e32 v0, v0, v52
	v_add_f32_e32 v36, v123, v36
	v_exp_f32_e32 v128, v0
	v_add_f32_e32 v36, v125, v36
	v_add_f32_e32 v36, v126, v36
	v_add_u32_e32 v124, 0x6800, v171
	v_add_u32_e32 v89, 0x8000, v171
	v_add_u32_e32 v91, 0x9800, v171
	v_add_f32_e32 v53, v127, v36
	ds_read2_b64 v[36:39], v93 offset0:64 offset1:68
	v_cvt_pk_bf16_f32 v41, v41, v42
	ds_read2_b64 v[44:47], v124 offset0:224 offset1:228
	v_cvt_pk_bf16_f32 v42, v43, v48
	v_cvt_pk_bf16_f32 v43, v49, v50
	ds_read2_b64 v[48:51], v89 offset0:128 offset1:132
	ds_read2_b64 v[56:59], v91 offset0:32 offset1:36
	v_add_f32_e32 v0, v128, v53
	v_cvt_pk_bf16_f32 v40, v1, v3
	ds_bpermute_b32 v1, v173, v0
	s_waitcnt lgkmcnt(0)
	v_add_f32_e32 v53, v0, v1
	ds_bpermute_b32 v54, v174, v53
	v_mfma_f32_16x16x32_bf16 v[36:39], v[36:39], v[40:43], 0
	v_mfma_f32_16x16x32_bf16 v[44:47], v[44:47], v[40:43], 0
	v_mfma_f32_16x16x32_bf16 v[48:51], v[48:51], v[40:43], 0
	v_mfma_f32_16x16x32_bf16 v[40:43], v[56:59], v[40:43], 0
	v_cvt_pk_bf16_f32 v56, v55, v60
	v_cvt_pk_bf16_f32 v57, v61, v62
	v_cvt_pk_bf16_f32 v58, v63, v66
	ds_read2_b64 v[60:63], v93 offset0:72 offset1:76
	v_cvt_pk_bf16_f32 v59, v68, v69
	s_waitcnt lgkmcnt(0)
	s_nop 0
	v_mfma_f32_16x16x32_bf16 v[36:39], v[60:63], v[56:59], v[36:39]
	ds_read2_b64 v[60:63], v124 offset0:232 offset1:236
	s_waitcnt lgkmcnt(0)
	v_mfma_f32_16x16x32_bf16 v[44:47], v[60:63], v[56:59], v[44:47]
	ds_read2_b64 v[60:63], v89 offset0:136 offset1:140
	s_waitcnt lgkmcnt(0)
	v_mfma_f32_16x16x32_bf16 v[48:51], v[60:63], v[56:59], v[48:51]
	ds_read2_b64 v[60:63], v91 offset0:40 offset1:44
	s_waitcnt lgkmcnt(0)
	v_mfma_f32_16x16x32_bf16 v[40:43], v[60:63], v[56:59], v[40:43]
	ds_read2_b64 v[60:63], v93 offset0:80 offset1:84
	v_cvt_pk_bf16_f32 v56, v70, v71
	v_cvt_pk_bf16_f32 v57, v72, v73
	v_cvt_pk_bf16_f32 v58, v74, v75
	v_cvt_pk_bf16_f32 v59, v114, v115
	s_waitcnt lgkmcnt(0)
	s_nop 0
	v_mfma_f32_16x16x32_bf16 v[36:39], v[60:63], v[56:59], v[36:39]
	ds_read2_b64 v[60:63], v124 offset0:240 offset1:244
	s_waitcnt lgkmcnt(0)
	v_mfma_f32_16x16x32_bf16 v[44:47], v[60:63], v[56:59], v[44:47]
	ds_read2_b64 v[60:63], v89 offset0:144 offset1:148
	s_waitcnt lgkmcnt(0)
	v_mfma_f32_16x16x32_bf16 v[48:51], v[60:63], v[56:59], v[48:51]
	ds_read2_b64 v[60:63], v91 offset0:48 offset1:52
	s_waitcnt lgkmcnt(0)
	v_mfma_f32_16x16x32_bf16 v[40:43], v[60:63], v[56:59], v[40:43]
	ds_read2_b64 v[60:63], v93 offset0:88 offset1:92
	v_cvt_pk_bf16_f32 v56, v116, v117
	v_cvt_pk_bf16_f32 v57, v118, v119
	v_cvt_pk_bf16_f32 v58, v120, v121
	v_cvt_pk_bf16_f32 v59, v122, v123
	s_waitcnt lgkmcnt(0)
	s_nop 0
	v_mfma_f32_16x16x32_bf16 v[36:39], v[60:63], v[56:59], v[36:39]
	ds_read2_b64 v[60:63], v124 offset0:248 offset1:252
	s_waitcnt lgkmcnt(0)
	v_mfma_f32_16x16x32_bf16 v[44:47], v[60:63], v[56:59], v[44:47]
	ds_read2_b64 v[60:63], v89 offset0:152 offset1:156
	s_waitcnt lgkmcnt(0)
	v_mfma_f32_16x16x32_bf16 v[60:63], v[60:63], v[56:59], v[48:51]
	s_nop 2
	ds_read2_b64 v[48:51], v91 offset0:56 offset1:60
	s_waitcnt lgkmcnt(0)
	v_mfma_f32_16x16x32_bf16 v[56:59], v[48:51], v[56:59], v[40:43]
	s_nop 2
	ds_read2_b64 v[40:43], v93 offset0:96 offset1:100
	v_cvt_pk_bf16_f32 v0, v125, v126
	v_cvt_pk_bf16_f32 v1, v127, v128
	v_mov_b32_e32 v3, v2
	v_add_u32_e32 v125, 0x7000, v171
	s_waitcnt lgkmcnt(0)
	v_mfma_f32_16x16x32_bf16 v[48:51], v[40:43], v[0:3], v[36:39]
	s_nop 2
	ds_read2_b64 v[36:39], v125 offset1:4
	s_waitcnt lgkmcnt(0)
	v_mfma_f32_16x16x32_bf16 v[44:47], v[36:39], v[0:3], v[44:47]
	ds_read2_b64 v[36:39], v89 offset0:160 offset1:164
	s_waitcnt lgkmcnt(0)
	v_mfma_f32_16x16x32_bf16 v[40:43], v[36:39], v[0:3], v[60:63]
	ds_read2_b64 v[36:39], v91 offset0:64 offset1:68
	s_waitcnt lgkmcnt(0)
	v_mfma_f32_16x16x32_bf16 v[36:39], v[36:39], v[0:3], v[56:59]
	v_or_b32_e32 v0, s70, v103
	s_movk_i32 s0, 0x810
	v_cmp_gt_i32_e32 vcc, s0, v0
	s_and_saveexec_b64 s[0:1], vcc
	s_cbranch_execz .LBB0_560
	v_sub_f32_e32 v0, v67, v52
	v_exp_f32_e32 v0, v0
	v_add_f32_e32 v1, v53, v54
	v_add_f32_e32 v3, v0, v1
	v_div_scale_f32 v52, s[4:5], v3, v3, 1.0
	v_rcp_f32_e32 v53, v52
	v_div_scale_f32 v54, vcc, 1.0, v3, 1.0
	v_lshl_add_u64 v[0:1], v[64:65], 0, v[112:113]
	v_fma_f32 v55, -v52, v53, 1.0
	v_fmac_f32_e32 v53, v55, v53
	v_mul_f32_e32 v55, v54, v53
	v_fma_f32 v56, -v52, v55, v54
	v_fmac_f32_e32 v55, v56, v53
	v_fma_f32 v52, -v52, v55, v54
	v_div_fmas_f32 v52, v52, v53, v55
	v_div_fixup_f32 v52, v52, v3, 1.0
	v_permlane16_swap_b32 v108, v110
	v_permlane16_swap_b32 v109, v111
	v_permlane16_swap_b32 v104, v106
	v_permlane16_swap_b32 v105, v107
	v_pk_mul_f32 v[48:49], v[52:53], v[48:49] op_sel_hi:[0,1]
	v_pk_mul_f32 v[50:51], v[52:53], v[50:51] op_sel_hi:[0,1]
	v_lshlrev_b32_e32 v54, 16, v110
	v_and_b32_e32 v55, 0xffff0000, v110
	v_pk_mul_f32 v[48:49], v[48:49], v[54:55]
	v_lshlrev_b32_e32 v54, 16, v111
	v_and_b32_e32 v55, 0xffff0000, v111
	v_pk_mul_f32 v[50:51], v[50:51], v[54:55]
	v_cvt_pk_bf16_f32 v48, v48, v49
	v_cvt_pk_bf16_f32 v49, v50, v51
	v_pk_mul_f32 v[44:45], v[52:53], v[44:45] op_sel_hi:[0,1]
	v_pk_mul_f32 v[46:47], v[52:53], v[46:47] op_sel_hi:[0,1]
	v_lshlrev_b32_e32 v54, 16, v108
	v_and_b32_e32 v55, 0xffff0000, v108
	v_pk_mul_f32 v[44:45], v[44:45], v[54:55]
	v_lshlrev_b32_e32 v54, 16, v109
	v_and_b32_e32 v55, 0xffff0000, v109
	v_pk_mul_f32 v[46:47], v[46:47], v[54:55]
	v_cvt_pk_bf16_f32 v50, v44, v45
	v_cvt_pk_bf16_f32 v51, v46, v47
	v_mbcnt_lo_u32_b32 v54, -1, 0
	v_mbcnt_hi_u32_b32 v54, -1, v54
	v_and_b32_e32 v54, 16, v54
	v_lshrrev_b32_e32 v55, 1, v54
	v_add_u32_e32 v54, v54, v55
	v_mov_b32_e32 v55, 0
	v_lshl_add_u64 v[0:1], v[54:55], 0, v[0:1]
	v_permlane16_swap_b32 v48, v50
	v_permlane16_swap_b32 v49, v51
	global_store_dwordx4 v[0:1], v[48:51], off
	v_pk_mul_f32 v[40:41], v[52:53], v[40:41] op_sel_hi:[0,1]
	v_pk_mul_f32 v[42:43], v[52:53], v[42:43] op_sel_hi:[0,1]
	v_lshlrev_b32_e32 v44, 16, v106
	v_and_b32_e32 v45, 0xffff0000, v106
	v_pk_mul_f32 v[40:41], v[40:41], v[44:45]
	v_lshlrev_b32_e32 v44, 16, v107
	v_and_b32_e32 v45, 0xffff0000, v107
	v_pk_mul_f32 v[42:43], v[42:43], v[44:45]
	v_cvt_pk_bf16_f32 v40, v40, v41
	v_cvt_pk_bf16_f32 v41, v42, v43
	v_pk_mul_f32 v[36:37], v[52:53], v[36:37] op_sel_hi:[0,1]
	v_pk_mul_f32 v[38:39], v[52:53], v[38:39] op_sel_hi:[0,1]
	v_lshlrev_b32_e32 v44, 16, v104
	v_and_b32_e32 v45, 0xffff0000, v104
	v_pk_mul_f32 v[36:37], v[36:37], v[44:45]
	v_lshlrev_b32_e32 v44, 16, v105
	v_and_b32_e32 v45, 0xffff0000, v105
	v_pk_mul_f32 v[38:39], v[38:39], v[44:45]
	v_cvt_pk_bf16_f32 v42, v36, v37
	v_cvt_pk_bf16_f32 v43, v38, v39
	s_nop 1
	v_permlane16_swap_b32 v40, v42
	v_permlane16_swap_b32 v41, v43
	global_store_dwordx4 v[0:1], v[40:43], off offset:64
	s_nop 1

.LBB0_564:
	v_sub_f32_e32 v3, v31, v66
	v_fmac_f32_e32 v3, 0x43130000, v102
	v_cndmask_b32_e64 v28, v214, v3, s[0:1]
	v_max_f32_e32 v3, v132, v132
	v_max_f32_e32 v3, v3, v28
	ds_bpermute_b32 v29, v173, v3
	ds_read2_b64 v[36:39], v124 offset0:224 offset1:228
	ds_read2_b64 v[40:43], v89 offset0:128 offset1:132
	ds_read2_b64 v[44:47], v91 offset0:32 offset1:36
	s_waitcnt lgkmcnt(3)
	v_max_f32_e32 v29, v29, v29
	v_max_f32_e32 v3, v3, v29
	ds_bpermute_b32 v29, v174, v3
	s_waitcnt lgkmcnt(0)
	v_max3_f32 v3, v3, v29, v67
	v_sub_f32_e32 v29, v127, v3
	v_exp_f32_e32 v29, v29
	v_sub_f32_e32 v30, v30, v3
	v_exp_f32_e32 v30, v30
	v_sub_f32_e32 v32, v128, v3
	v_exp_f32_e32 v32, v32
	v_sub_f32_e32 v33, v126, v3
	v_exp_f32_e32 v33, v33
	v_sub_f32_e32 v34, v104, v3
	v_add_f32_e32 v31, 0, v29
	v_exp_f32_e32 v48, v34
	v_sub_f32_e32 v34, v105, v3
	v_add_f32_e32 v31, v30, v31
	v_exp_f32_e32 v49, v34
	v_sub_f32_e32 v0, v0, v3
	v_add_f32_e32 v31, v32, v31
	v_exp_f32_e32 v50, v0
	v_sub_f32_e32 v1, v1, v3
	v_add_f32_e32 v31, v33, v31
	v_exp_f32_e32 v51, v1
	v_sub_f32_e32 v1, v68, v3
	v_add_f32_e32 v31, v48, v31
	v_exp_f32_e32 v52, v1
	v_sub_f32_e32 v1, v69, v3
	v_add_f32_e32 v31, v49, v31
	v_exp_f32_e32 v53, v1
	v_sub_f32_e32 v1, v70, v3
	v_add_f32_e32 v0, v50, v31
	v_exp_f32_e32 v54, v1
	v_sub_f32_e32 v1, v71, v3
	v_add_f32_e32 v0, v51, v0
	v_exp_f32_e32 v55, v1
	v_sub_f32_e32 v1, v72, v3
	v_add_f32_e32 v0, v52, v0
	v_exp_f32_e32 v56, v1
	v_sub_f32_e32 v1, v73, v3
	v_add_f32_e32 v0, v53, v0
	v_exp_f32_e32 v57, v1
	v_sub_f32_e32 v1, v74, v3
	v_add_f32_e32 v0, v54, v0
	v_exp_f32_e32 v58, v1
	v_sub_f32_e32 v1, v75, v3
	v_add_f32_e32 v0, v55, v0
	v_exp_f32_e32 v59, v1
	v_sub_f32_e32 v1, v106, v3
	v_add_f32_e32 v0, v56, v0
	v_exp_f32_e32 v60, v1
	v_sub_f32_e32 v1, v107, v3
	v_add_f32_e32 v0, v57, v0
	v_exp_f32_e32 v61, v1
	v_sub_f32_e32 v1, v110, v3
	v_add_f32_e32 v0, v58, v0
	v_exp_f32_e32 v62, v1
	v_sub_f32_e32 v1, v111, v3
	v_add_f32_e32 v0, v59, v0
	v_exp_f32_e32 v63, v1
	v_sub_f32_e32 v1, v112, v3
	v_add_f32_e32 v0, v60, v0
	v_exp_f32_e32 v66, v1
	v_sub_f32_e32 v1, v113, v3
	v_add_f32_e32 v0, v61, v0
	v_exp_f32_e32 v68, v1
	v_sub_f32_e32 v1, v114, v3
	v_add_f32_e32 v0, v62, v0
	v_exp_f32_e32 v69, v1
	v_sub_f32_e32 v1, v115, v3
	v_add_f32_e32 v0, v63, v0
	v_exp_f32_e32 v70, v1
	v_sub_f32_e32 v1, v116, v3
	v_add_f32_e32 v0, v66, v0
	v_exp_f32_e32 v71, v1
	v_sub_f32_e32 v1, v117, v3
	v_add_f32_e32 v0, v68, v0
	v_exp_f32_e32 v72, v1
	v_sub_f32_e32 v1, v118, v3
	v_add_f32_e32 v0, v69, v0
	v_exp_f32_e32 v73, v1
	v_sub_f32_e32 v1, v119, v3
	v_add_f32_e32 v0, v70, v0
	v_exp_f32_e32 v74, v1
	v_sub_f32_e32 v1, v120, v3
	v_add_f32_e32 v0, v71, v0
	v_exp_f32_e32 v75, v1
	v_sub_f32_e32 v1, v121, v3
	v_add_f32_e32 v0, v72, v0
	v_exp_f32_e32 v102, v1
	v_sub_f32_e32 v1, v122, v3
	v_add_f32_e32 v0, v73, v0
	v_exp_f32_e32 v104, v1
	v_sub_f32_e32 v1, v123, v3
	v_add_f32_e32 v0, v74, v0
	v_exp_f32_e32 v105, v1
	v_sub_f32_e32 v1, v131, v3
	v_add_f32_e32 v0, v75, v0
	v_exp_f32_e32 v106, v1
	v_sub_f32_e32 v1, v129, v3
	v_add_f32_e32 v0, v102, v0
	v_exp_f32_e32 v107, v1
	v_sub_f32_e32 v1, v130, v3
	v_add_f32_e32 v0, v104, v0
	v_exp_f32_e32 v108, v1
	v_sub_f32_e32 v1, v28, v3
	v_add_f32_e32 v0, v105, v0
	v_exp_f32_e32 v109, v1
	v_add_f32_e32 v0, v106, v0
	v_add_f32_e32 v0, v107, v0
	v_add_f32_e32 v0, v108, v0
	v_cvt_pk_bf16_f32 v31, v32, v33
	ds_read2_b64 v[32:35], v93 offset0:64 offset1:68
	v_add_f32_e32 v0, v109, v0
	ds_bpermute_b32 v1, v173, v0
	v_cvt_pk_bf16_f32 v30, v29, v30
	v_mov_b32_e32 v28, v2
	v_mov_b32_e32 v29, v2
	s_waitcnt lgkmcnt(0)
	v_add_f32_e32 v0, v0, v1
	ds_bpermute_b32 v1, v174, v0
	v_mfma_f32_16x16x32_bf16 v[32:35], v[32:35], v[28:31], 0
	v_mfma_f32_16x16x32_bf16 v[36:39], v[36:39], v[28:31], 0
	v_mfma_f32_16x16x32_bf16 v[40:43], v[40:43], v[28:31], 0
	v_mfma_f32_16x16x32_bf16 v[28:31], v[44:47], v[28:31], 0
	v_cvt_pk_bf16_f32 v44, v48, v49
	v_cvt_pk_bf16_f32 v45, v50, v51
	ds_read2_b64 v[48:51], v93 offset0:72 offset1:76
	v_cvt_pk_bf16_f32 v46, v52, v53
	v_cvt_pk_bf16_f32 v47, v54, v55
	s_waitcnt lgkmcnt(0)
	s_nop 0
	v_mfma_f32_16x16x32_bf16 v[32:35], v[48:51], v[44:47], v[32:35]
	ds_read2_b64 v[48:51], v124 offset0:232 offset1:236
	s_waitcnt lgkmcnt(0)
	v_mfma_f32_16x16x32_bf16 v[36:39], v[48:51], v[44:47], v[36:39]
	ds_read2_b64 v[48:51], v89 offset0:136 offset1:140
	s_waitcnt lgkmcnt(0)
	v_mfma_f32_16x16x32_bf16 v[40:43], v[48:51], v[44:47], v[40:43]
	ds_read2_b64 v[48:51], v91 offset0:40 offset1:44
	s_waitcnt lgkmcnt(0)
	v_mfma_f32_16x16x32_bf16 v[28:31], v[48:51], v[44:47], v[28:31]
	ds_read2_b64 v[48:51], v93 offset0:80 offset1:84
	v_cvt_pk_bf16_f32 v44, v56, v57
	v_cvt_pk_bf16_f32 v45, v58, v59
	v_cvt_pk_bf16_f32 v46, v60, v61
	v_cvt_pk_bf16_f32 v47, v62, v63
	s_waitcnt lgkmcnt(0)
	s_nop 0
	v_mfma_f32_16x16x32_bf16 v[32:35], v[48:51], v[44:47], v[32:35]
	ds_read2_b64 v[48:51], v124 offset0:240 offset1:244
	s_waitcnt lgkmcnt(0)
	v_mfma_f32_16x16x32_bf16 v[36:39], v[48:51], v[44:47], v[36:39]
	ds_read2_b64 v[48:51], v89 offset0:144 offset1:148
	s_waitcnt lgkmcnt(0)
	v_mfma_f32_16x16x32_bf16 v[40:43], v[48:51], v[44:47], v[40:43]
	ds_read2_b64 v[48:51], v91 offset0:48 offset1:52
	s_waitcnt lgkmcnt(0)
	v_mfma_f32_16x16x32_bf16 v[28:31], v[48:51], v[44:47], v[28:31]
	ds_read2_b64 v[48:51], v93 offset0:88 offset1:92
	v_cvt_pk_bf16_f32 v44, v66, v68
	v_cvt_pk_bf16_f32 v45, v69, v70
	v_cvt_pk_bf16_f32 v46, v71, v72
	v_cvt_pk_bf16_f32 v47, v73, v74
	s_waitcnt lgkmcnt(0)
	s_nop 0
	v_mfma_f32_16x16x32_bf16 v[32:35], v[48:51], v[44:47], v[32:35]
	ds_read2_b64 v[48:51], v124 offset0:248 offset1:252
	s_waitcnt lgkmcnt(0)
	v_mfma_f32_16x16x32_bf16 v[36:39], v[48:51], v[44:47], v[36:39]
	ds_read2_b64 v[48:51], v89 offset0:152 offset1:156
	s_waitcnt lgkmcnt(0)
	v_mfma_f32_16x16x32_bf16 v[48:51], v[48:51], v[44:47], v[40:43]
	s_nop 2
	ds_read2_b64 v[40:43], v91 offset0:56 offset1:60
	s_waitcnt lgkmcnt(0)
	v_mfma_f32_16x16x32_bf16 v[28:31], v[40:43], v[44:47], v[28:31]
	ds_read2_b64 v[40:43], v93 offset0:96 offset1:100
	v_cvt_pk_bf16_f32 v44, v75, v102
	v_cvt_pk_bf16_f32 v45, v104, v105
	v_cvt_pk_bf16_f32 v46, v106, v107
	v_cvt_pk_bf16_f32 v47, v108, v109
	s_waitcnt lgkmcnt(0)
	s_nop 0
	v_mfma_f32_16x16x32_bf16 v[40:43], v[40:43], v[44:47], v[32:35]
	s_nop 2
	ds_read2_b64 v[32:35], v125 offset1:4
	s_waitcnt lgkmcnt(0)
	v_mfma_f32_16x16x32_bf16 v[36:39], v[32:35], v[44:47], v[36:39]
	ds_read2_b64 v[32:35], v89 offset0:160 offset1:164
	s_waitcnt lgkmcnt(0)
	v_mfma_f32_16x16x32_bf16 v[32:35], v[32:35], v[44:47], v[48:51]
	s_nop 2
	ds_read2_b64 v[48:51], v91 offset0:64 offset1:68
	s_waitcnt lgkmcnt(0)
	v_mfma_f32_16x16x32_bf16 v[28:31], v[48:51], v[44:47], v[28:31]
	v_or_b32_e32 v44, s70, v153
	s_movk_i32 s0, 0x810
	v_cmp_gt_i32_e32 vcc, s0, v44
	s_and_saveexec_b64 s[0:1], vcc
	s_cbranch_execz .LBB0_547
	v_sub_f32_e32 v3, v67, v3
	v_exp_f32_e32 v3, v3
	v_add_f32_e32 v0, v0, v1
	v_and_b32_e32 v47, 0xffff0000, v100
	v_add_f32_e32 v0, v3, v0
	v_div_scale_f32 v1, s[4:5], v0, v0, 1.0
	v_rcp_f32_e32 v3, v1
	s_nop 0
	v_fma_f32 v44, -v1, v3, 1.0
	v_fmac_f32_e32 v3, v44, v3
	v_div_scale_f32 v44, vcc, 1.0, v0, 1.0
	v_mul_f32_e32 v45, v44, v3
	v_fma_f32 v46, -v1, v45, v44
	v_fmac_f32_e32 v45, v46, v3
	v_fma_f32 v1, -v1, v45, v44
	v_div_fmas_f32 v1, v1, v3, v45
	v_div_fixup_f32 v0, v1, v0, 1.0
	v_add_u32_e32 v44, s60, v153
	v_ashrrev_i32_e32 v45, 31, v44
	v_lshlrev_b64 v[44:45], 13, v[44:45]
	v_lshl_add_u64 v[44:45], v[64:65], 0, v[44:45]
	v_permlane16_swap_b32 v98, v100
	v_permlane16_swap_b32 v99, v101
	v_permlane16_swap_b32 v94, v96
	v_permlane16_swap_b32 v95, v97
	v_pk_mul_f32 v[40:41], v[0:1], v[40:41] op_sel_hi:[0,1]
	v_pk_mul_f32 v[42:43], v[0:1], v[42:43] op_sel_hi:[0,1]
	v_lshlrev_b32_e32 v46, 16, v100
	v_and_b32_e32 v47, 0xffff0000, v100
	v_pk_mul_f32 v[40:41], v[40:41], v[46:47]
	v_lshlrev_b32_e32 v46, 16, v101
	v_and_b32_e32 v47, 0xffff0000, v101
	v_pk_mul_f32 v[42:43], v[42:43], v[46:47]
	v_cvt_pk_bf16_f32 v40, v40, v41
	v_cvt_pk_bf16_f32 v41, v42, v43
	v_pk_mul_f32 v[36:37], v[0:1], v[36:37] op_sel_hi:[0,1]
	v_pk_mul_f32 v[38:39], v[0:1], v[38:39] op_sel_hi:[0,1]
	v_lshlrev_b32_e32 v46, 16, v98
	v_and_b32_e32 v47, 0xffff0000, v98
	v_pk_mul_f32 v[36:37], v[36:37], v[46:47]
	v_lshlrev_b32_e32 v46, 16, v99
	v_and_b32_e32 v47, 0xffff0000, v99
	v_pk_mul_f32 v[38:39], v[38:39], v[46:47]
	v_cvt_pk_bf16_f32 v42, v36, v37
	v_cvt_pk_bf16_f32 v43, v38, v39
	v_mbcnt_lo_u32_b32 v46, -1, 0
	v_mbcnt_hi_u32_b32 v46, -1, v46
	v_and_b32_e32 v46, 16, v46
	v_lshrrev_b32_e32 v47, 1, v46
	v_add_u32_e32 v46, v46, v47
	v_mov_b32_e32 v47, 0
	v_lshl_add_u64 v[44:45], v[46:47], 0, v[44:45]
	v_permlane16_swap_b32 v40, v42
	v_permlane16_swap_b32 v41, v43
	global_store_dwordx4 v[44:45], v[40:43], off
	v_pk_mul_f32 v[32:33], v[0:1], v[32:33] op_sel_hi:[0,1]
	v_pk_mul_f32 v[34:35], v[0:1], v[34:35] op_sel_hi:[0,1]
	v_pk_mul_f32 v[28:29], v[0:1], v[28:29] op_sel_hi:[0,1]
	v_pk_mul_f32 v[30:31], v[0:1], v[30:31] op_sel_hi:[0,1]
	v_lshlrev_b32_e32 v36, 16, v96
	v_and_b32_e32 v37, 0xffff0000, v96
	v_pk_mul_f32 v[32:33], v[32:33], v[36:37]
	v_lshlrev_b32_e32 v36, 16, v97
	v_and_b32_e32 v37, 0xffff0000, v97
	v_pk_mul_f32 v[34:35], v[34:35], v[36:37]
	v_cvt_pk_bf16_f32 v32, v32, v33
	v_cvt_pk_bf16_f32 v33, v34, v35
	v_lshlrev_b32_e32 v36, 16, v94
	v_and_b32_e32 v37, 0xffff0000, v94
	v_pk_mul_f32 v[28:29], v[28:29], v[36:37]
	v_lshlrev_b32_e32 v36, 16, v95
	v_and_b32_e32 v37, 0xffff0000, v95
	v_pk_mul_f32 v[30:31], v[30:31], v[36:37]
	v_cvt_pk_bf16_f32 v34, v28, v29
	v_cvt_pk_bf16_f32 v35, v30, v31
	s_nop 1
	v_permlane16_swap_b32 v32, v34
	v_permlane16_swap_b32 v33, v35
	global_store_dwordx4 v[44:45], v[32:35], off offset:64
	s_nop 1
	s_branch .LBB0_547
